# v20: + odd workgroups run conv pre-pass and FFN weight copies before their attention units (memory phase of one half overlaps attention of the other), on top of v19
# baseline (speedup 1.0000x reference)
; #define XBAR() do { XcdBarrier xb_; xb_.bar = (unsigned*)(ws + WS_XBAR); xb_.x = xb_xcc_id(); xb_.st = (volatile LAS unsigned*)(lds + LDS_XB_ST); xcd_barrier(xb_); } while (0)
; __global__ void __launch_bounds__(512, 2) fwd(Args a) {
;     ...
;     if (IN(2)) {
;     ...
;         P2_BODY(Qb, DUP_PART, 1); XBAR();
;     ...
;         P2_BODY(Qb, 2, 0);
;         P2_BODY(Qb, 5, 0);
.LBB0_356:
	s_cmp_lt_i32 s16, 3
	s_cselect_b64 s[4:5], -1, 0
	s_add_u32 s21, s14, 0x12800000
	s_addc_u32 s23, s15, 0
	s_add_u32 s6, s14, 0x16800000
	s_addc_u32 s7, s15, 0
	s_and_b64 s[28:29], s[4:5], s[2:3]
	s_andn2_b64 vcc, exec, s[28:29]
	s_cbranch_vccnz .LBB0_488
	s_cmpk_gt_i32 s33, 0xff
	s_cbranch_scc1 .LBB0_420
	s_bitcmp1_b32 s33, 0
	s_cbranch_scc0 .Lp2_attn
	s_mov_b64 s[98:99], s[48:49]
	s_mov_b64 s[100:101], s[50:51]
	s_branch .LBB0_420
.Lp2_attn:
	s_ashr_i32 s2, s33, 6
	s_lshl_b32 s4, s33, 5
	s_ashr_i32 s3, s2, 31
	s_and_b32 s11, s4, 0x780
	s_and_b32 s91, s33, 3
	s_lshl_b64 s[8:9], s[2:3], 12
	s_lshl_b32 s34, s11, 1
	s_add_u32 s27, s21, s34
	s_addc_u32 s86, s23, 0
	s_lshl_b64 s[4:5], s[2:3], 24
	s_add_u32 s35, s6, s4
	s_addc_u32 s53, s7, s5
	s_add_u32 s52, s35, s34
	s_addc_u32 s53, s53, 0
	s_lshl_b32 s60, s11, 15
	s_add_u32 s50, s50, s60
	s_addc_u32 s51, s51, 0
	s_lshl_b64 s[34:35], s[2:3], 13
	s_add_u32 s50, s50, s34
	s_addc_u32 s51, s51, s35
	s_lshl_b32 s2, s2, 4
	s_ashr_i32 s3, s2, 31
	s_lshl_b64 s[2:3], s[2:3], 13
	s_add_u32 s2, s48, s2
	s_addc_u32 s3, s49, s3
	s_lshl_b32 s11, s11, 2
	s_add_u32 s48, s2, s11
	s_addc_u32 s49, s3, 0
	s_xor_b32 s24, s91, 7
	s_or_b32 s25, s91, 8
	s_xor_b32 s36, s91, 15
	s_add_u32 s56, s52, 0x40000
	s_addc_u32 s57, s53, 0
	s_lshl_b32 s2, s33, 6
	s_and_b32 s2, s2, 0xf00
	s_or_b32 s2, s4, s2
	s_add_u32 s58, s2, 0x16880000
	s_addc_u32 s59, s5, 0
	s_add_u32 s2, s60, s34
	s_addc_u32 s3, 0, s35
	s_add_u32 s60, s2, 0x1a800100
	v_mbcnt_lo_u32_b32 v1, -1, 0
	s_mov_b32 s26, 0
	s_mov_b64 s[54:55], 0x40000
	s_addc_u32 s61, s3, 0
	s_movk_i32 s92, 0xf0
	s_movk_i32 s93, 0x70
	s_movk_i32 s94, 0x8000
	s_waitcnt lgkmcnt(0)
	v_mov_b32_e32 v3, 0
	s_mov_b64 s[62:63], 0x80
	s_add_i32 s37, 0, 0x18000
	s_add_i32 s38, 0, 0x18800
	s_movk_i32 s97, 0x60
	v_mbcnt_hi_u32_b32 v1, -1, v1
	v_mov_b32_e32 v254, 0x800
	v_mov_b32_e32 v230, 0x2000
	v_mov_b32_e32 v231, 0x4000
	v_mov_b32_e32 v232, 0xf149f2ca
	v_mov_b32_e32 v233, 0x7149f2ca
	s_branch .LBB0_360

; #define XBAR() do { XcdBarrier xb_; xb_.bar = (unsigned*)(ws + WS_XBAR); xb_.x = xb_xcc_id(); xb_.st = (volatile LAS unsigned*)(lds + LDS_XB_ST); xcd_barrier(xb_); } while (0)
; __global__ void __launch_bounds__(512, 2) fwd(Args a) {
;     ...
;         P2_BODY(Qb, 2, 0);
;         P2_BODY(Qb, 5, 0);
;     }
;     if (IN(2)) XBAR();
.Lp2_attn_done:
	s_bitcmp1_b32 s33, 0
	s_cbranch_scc1 .Lp2_xbar

; #define XBAR() do { XcdBarrier xb_; xb_.bar = (unsigned*)(ws + WS_XBAR); xb_.x = xb_xcc_id(); xb_.st = (volatile LAS unsigned*)(lds + LDS_XB_ST); xcd_barrier(xb_); } while (0)
; __global__ void __launch_bounds__(512, 2) fwd(Args a) {
;     ...
;     if (IN(2)) {
;     ...
;         P2_BODY(Qb, DUP_PART, 1); XBAR();
;     ...
;         P2_BODY(Qb, 2, 0);
;         P2_BODY(Qb, 5, 0);
;     }
;     if (IN(2)) XBAR();
.LBB0_435:
	s_bitcmp1_b32 s33, 0
	s_cbranch_scc0 .Lp2_xbar
	s_mov_b64 s[48:49], s[98:99]
	s_mov_b64 s[50:51], s[100:101]
	s_waitcnt vmcnt(0) lgkmcnt(0)
	s_barrier
	s_branch .Lp2_attn
